# v36 with accumulator re-zeroing through LDS (32 broadcast ds_read_b128 of a zero chunk) instead of 63 v_mov_b64
# speedup vs baseline: 1.0106x; 1.0005x over previous
; #define LAS __attribute__((address_space(3)))
; __device__ __forceinline__ unsigned xb_add(unsigned* p, unsigned v) { return __hip_atomic_fetch_add(p, v, __ATOMIC_RELAXED, __HIP_MEMORY_SCOPE_AGENT); }
; __device__ __forceinline__ unsigned xb_xcc_id() { return (unsigned)__builtin_amdgcn_s_getreg((3 << 11) | 20) & 0xFu; }
; __device__ __forceinline__ XcdBarrier xcd_barrier_post(unsigned* bar, volatile LAS unsigned* st) {
;     XcdBarrier b; b.bar = bar; b.x = xb_xcc_id(); b.st = st;
;     if (threadIdx.x == 0) (void)xb_add(&bar[XB_XCNT(b.x)], 1u);
;     return b;
; __global__ void __launch_bounds__(512, 2) mega_fwd(Args a) {
;     ...
;     unsigned char* ws = a.ws;
;     LAS unsigned char* ldsl = (LAS unsigned char*)lds;
;     unsigned long long* rssb = (unsigned long long*)(ws + WS_RSS);
;     volatile LAS unsigned* bst = (volatile LAS unsigned*)(ldsl + (LDS_BYTES - 64));
;     if (threadIdx.x < 2) bst[threadIdx.x] = 0u;
;     __syncthreads();
;     XcdBarrier bar = xcd_barrier_post((unsigned*)(ws + WS_BAR), bst);
_Z8mega_fwd4Args:
	s_load_dwordx8 s[80:87], s[0:1], 0xe0
	s_load_dwordx8 s[4:11], s[0:1], 0xc0
	v_and_b32_e32 v174, 0x3ff, v0
	v_cmp_gt_u32_e32 vcc, 2, v174
	s_waitcnt lgkmcnt(0)
	v_writelane_b32 v249, s4, 0
	s_nop 1
	v_writelane_b32 v249, s5, 1
	v_writelane_b32 v249, s6, 2
	v_writelane_b32 v249, s7, 3
	v_writelane_b32 v249, s8, 4
	v_writelane_b32 v249, s9, 5
	v_writelane_b32 v249, s10, 6
	v_writelane_b32 v249, s11, 7
	s_add_u32 s6, s0, 0xf8
	s_addc_u32 s7, s1, 0
	s_and_saveexec_b64 s[4:5], vcc
	v_lshl_add_u32 v1, v174, 2, 0
	v_add_u32_e32 v1, 0x23fc0, v1
	v_mov_b32_e32 v2, 0
	ds_write_b32 v1, v2
	s_or_b64 exec, exec, s[4:5]
	v_mov_b32_e32 v2, 0
	v_mov_b32_e32 v3, 0
	v_mov_b32_e32 v4, 0
	v_mov_b32_e32 v5, 0
	v_mov_b32_e32 v1, 0x23000
	ds_write_b128 v1, v[2:5]
	s_waitcnt lgkmcnt(0)
	s_barrier
	s_add_u32 s12, s82, 0xe0000
	s_getreg_b32 s3, hwreg(HW_REG_XCC_ID, 0, 4)
	s_addc_u32 s13, s83, 0
	s_and_b32 s3, s3, 15
	v_cmp_eq_u32_e64 s[20:21], 0, v174
	s_and_saveexec_b64 s[4:5], s[20:21]
	s_cbranch_execz .LBB0_5
	s_mov_b64 s[8:9], exec
	v_mbcnt_lo_u32_b32 v1, s8, 0
	v_mbcnt_hi_u32_b32 v1, s9, v1
	v_cmp_eq_u32_e32 vcc, 0, v1
	s_and_b64 s[10:11], exec, vcc
	s_mov_b64 exec, s[10:11]
	s_cbranch_execz .LBB0_5
	s_lshl_b32 s10, s3, 8
	s_bcnt1_i32_b64 s8, s[8:9]
	v_mov_b32_e32 v1, s10
	v_mov_b32_e32 v2, s8
	global_atomic_add v1, v2, s[12:13] offset:1024

;     __device__ bool next(int i, Unit& u) const { const bool ok = StaticOrder::next(i / 3, u); u.seg = i % 3; return ok; }
; template <class Epi, class Sched>
; __device__ __forceinline__ void gemm_phase(LAS unsigned char* lds, const Gemm g, const Sched& S, const Epi& E) {
;     ...
;         const bool has_next = S.next(ui + 1, nxt);
;         const char* nA = has_next ? (const char*)g.A + (size_t)(g.fix ? 0 : nxt.pm) * tstepA + (size_t)S.koff(nxt) * 2 : cA; const char* nB = has_next ? (const char*)g.Bt + (size_t)(g.fix ? 0 : nxt.pn) * tstepB + (size_t)S.koff(nxt) * 2 : cB;
;     ...
; #pragma unroll
;         for (int a = 0; a < 2; ++a)
; #pragma unroll
;             for (int b = 0; b < 2; ++b)
; #pragma unroll
;                 for (int m = 0; m < 4; ++m)
; #pragma unroll
;                     for (int n = 0; n < 2; ++n) acc[a][b][m][n] = (f32x4){0.f, 0.f, 0.f, 0.f};
;         cur = nxt; cA = nA; cB = nB; ++ui;
;         if (Sched::SEGMENTED) nt = S.nt(cur);
.LBB0_97:
	s_ashr_i32 s47, s46, 31
	s_lshl_b64 s[50:51], s[46:47], 20
	s_add_u32 s50, s72, s50
	s_addc_u32 s51, s73, s51
	s_and_b64 s[52:53], s[40:41], exec
	s_cselect_b32 s27, s51, s23
	s_cselect_b32 s47, s50, s22
	s_ashr_i32 s49, s48, 31
	s_lshl_b64 s[52:53], s[48:49], 20
	v_readlane_b32 s56, v252, 57
	v_readlane_b32 s57, v252, 58
	s_add_u32 s52, s56, s52
	s_addc_u32 s53, s57, s53
	s_and_b64 s[56:57], s[40:41], exec
	s_cselect_b32 s49, s53, s55
	s_cselect_b32 s61, s52, s54
	s_add_u32 s22, s22, 0x80080
	s_addc_u32 s23, s23, 0
	s_add_u32 s65, s54, 0x100
	v_mov_b32_e32 v0, 0
	s_addc_u32 s92, s55, 0
	s_mov_b32 s94, -2
	s_waitcnt lgkmcnt(0)
	v_mov_b32_e32 v206, 0x23000
	ds_read_b128 v[0:3], v206
	ds_read_b128 v[4:7], v206
	ds_read_b128 v[8:11], v206
	ds_read_b128 v[12:15], v206
	ds_read_b128 v[16:19], v206
	ds_read_b128 v[20:23], v206
	ds_read_b128 v[24:27], v206
	ds_read_b128 v[28:31], v206
	ds_read_b128 v[32:35], v206
	ds_read_b128 v[36:39], v206
	ds_read_b128 v[40:43], v206
	ds_read_b128 v[44:47], v206
	ds_read_b128 v[48:51], v206
	ds_read_b128 v[52:55], v206
	ds_read_b128 v[56:59], v206
	ds_read_b128 v[60:63], v206
	ds_read_b128 v[64:67], v206
	ds_read_b128 v[68:71], v206
	ds_read_b128 v[72:75], v206
	ds_read_b128 v[76:79], v206
	ds_read_b128 v[80:83], v206
	ds_read_b128 v[84:87], v206
	ds_read_b128 v[88:91], v206
	ds_read_b128 v[92:95], v206
	ds_read_b128 v[96:99], v206
	ds_read_b128 v[100:103], v206
	ds_read_b128 v[104:107], v206
	ds_read_b128 v[108:111], v206
	ds_read_b128 v[112:115], v206
	ds_read_b128 v[116:119], v206
	ds_read_b128 v[120:123], v206
	ds_read_b128 v[124:127], v206

;     __device__ bool next(int i, Unit& u) const { const bool ok = StaticOrder::next(i / 3, u); u.seg = i % 3; return ok; }
; template <class Epi, class Sched>
; __device__ __forceinline__ void gemm_phase(LAS unsigned char* lds, const Gemm g, const Sched& S, const Epi& E) {
;     ...
;         const bool has_next = S.next(ui + 1, nxt);
;         const char* nA = has_next ? (const char*)g.A + (size_t)(g.fix ? 0 : nxt.pm) * tstepA + (size_t)S.koff(nxt) * 2 : cA; const char* nB = has_next ? (const char*)g.Bt + (size_t)(g.fix ? 0 : nxt.pn) * tstepB + (size_t)S.koff(nxt) * 2 : cB;
;     ...
; #pragma unroll
;         for (int a = 0; a < 2; ++a)
; #pragma unroll
;             for (int b = 0; b < 2; ++b)
; #pragma unroll
;                 for (int m = 0; m < 4; ++m)
; #pragma unroll
;                     for (int n = 0; n < 2; ++n) acc[a][b][m][n] = (f32x4){0.f, 0.f, 0.f, 0.f};
;         cur = nxt; cA = nA; cB = nB; ++ui;
;         if (Sched::SEGMENTED) nt = S.nt(cur);
.LBB0_140:
	s_add_i32 s20, s61, -2
	s_add_u32 s22, s22, 0x80080
	s_addc_u32 s23, s23, 0
	s_add_u32 s27, s40, 0x100
	v_mov_b32_e32 v0, 0
	s_addc_u32 s47, s41, 0
	s_mov_b32 s4, 0
	v_mov_b32_e32 v206, 0x23000
	ds_read_b128 v[0:3], v206
	ds_read_b128 v[4:7], v206
	ds_read_b128 v[8:11], v206
	ds_read_b128 v[12:15], v206
	ds_read_b128 v[16:19], v206
	ds_read_b128 v[20:23], v206
	ds_read_b128 v[24:27], v206
	ds_read_b128 v[28:31], v206
	ds_read_b128 v[32:35], v206
	ds_read_b128 v[36:39], v206
	ds_read_b128 v[40:43], v206
	ds_read_b128 v[44:47], v206
	ds_read_b128 v[48:51], v206
	ds_read_b128 v[52:55], v206
	ds_read_b128 v[56:59], v206
	ds_read_b128 v[60:63], v206
	ds_read_b128 v[64:67], v206
	ds_read_b128 v[68:71], v206
	ds_read_b128 v[72:75], v206
	ds_read_b128 v[76:79], v206
	ds_read_b128 v[80:83], v206
	ds_read_b128 v[84:87], v206
	ds_read_b128 v[88:91], v206
	ds_read_b128 v[92:95], v206
	ds_read_b128 v[96:99], v206
	ds_read_b128 v[100:103], v206
	ds_read_b128 v[104:107], v206
	ds_read_b128 v[108:111], v206
	ds_read_b128 v[112:115], v206
	ds_read_b128 v[116:119], v206
	ds_read_b128 v[120:123], v206
	ds_read_b128 v[124:127], v206

;     __device__ bool next(int i, Unit& u) const { const bool ok = StaticOrder::next(i / 3, u); u.seg = i % 3; return ok; }
; template <class Epi, class Sched>
; __device__ __forceinline__ void gemm_phase(LAS unsigned char* lds, const Gemm g, const Sched& S, const Epi& E) {
;     ...
;         const bool has_next = S.next(ui + 1, nxt);
;         const char* nA = has_next ? (const char*)g.A + (size_t)(g.fix ? 0 : nxt.pm) * tstepA + (size_t)S.koff(nxt) * 2 : cA; const char* nB = has_next ? (const char*)g.Bt + (size_t)(g.fix ? 0 : nxt.pn) * tstepB + (size_t)S.koff(nxt) * 2 : cB;
;     ...
; #pragma unroll
;         for (int a = 0; a < 2; ++a)
; #pragma unroll
;             for (int b = 0; b < 2; ++b)
; #pragma unroll
;                 for (int m = 0; m < 4; ++m)
; #pragma unroll
;                     for (int n = 0; n < 2; ++n) acc[a][b][m][n] = (f32x4){0.f, 0.f, 0.f, 0.f};
;         cur = nxt; cA = nA; cB = nB; ++ui;
;         if (Sched::SEGMENTED) nt = S.nt(cur);
.LBB0_196:
	s_ashr_i32 s41, s40, 31
	s_lshl_b64 s[44:45], s[40:41], 18
	s_add_u32 s44, s74, s44
	s_addc_u32 s45, s75, s45
	s_and_b64 s[46:47], s[38:39], exec
	s_cselect_b32 s27, s45, s49
	s_cselect_b32 s41, s44, s48
	s_ashr_i32 s43, s42, 31
	s_lshl_b64 s[46:47], s[42:43], 18
	v_readlane_b32 s52, v252, 35
	v_readlane_b32 s53, v252, 36
	s_add_u32 s46, s52, s46
	s_addc_u32 s47, s53, s47
	s_and_b64 s[52:53], s[38:39], exec
	s_cselect_b32 s43, s47, s51
	s_cselect_b32 s60, s46, s50
	s_add_u32 s48, s48, 0x20080
	s_addc_u32 s49, s49, 0
	s_add_u32 s61, s50, 0x100
	v_mov_b32_e32 v0, 0
	s_addc_u32 s62, s51, 0
	s_mov_b32 s63, -2
	v_mov_b32_e32 v206, 0x23000
	ds_read_b128 v[0:3], v206
	ds_read_b128 v[4:7], v206
	ds_read_b128 v[8:11], v206
	ds_read_b128 v[12:15], v206
	ds_read_b128 v[16:19], v206
	ds_read_b128 v[20:23], v206
	ds_read_b128 v[24:27], v206
	ds_read_b128 v[28:31], v206
	ds_read_b128 v[32:35], v206
	ds_read_b128 v[36:39], v206
	ds_read_b128 v[40:43], v206
	ds_read_b128 v[44:47], v206
	ds_read_b128 v[48:51], v206
	ds_read_b128 v[52:55], v206
	ds_read_b128 v[56:59], v206
	ds_read_b128 v[60:63], v206
	ds_read_b128 v[64:67], v206
	ds_read_b128 v[68:71], v206
	ds_read_b128 v[72:75], v206
	ds_read_b128 v[76:79], v206
	ds_read_b128 v[80:83], v206
	ds_read_b128 v[84:87], v206
	ds_read_b128 v[88:91], v206
	ds_read_b128 v[92:95], v206
	ds_read_b128 v[96:99], v206
	ds_read_b128 v[100:103], v206
	ds_read_b128 v[104:107], v206
	ds_read_b128 v[108:111], v206
	ds_read_b128 v[112:115], v206
	ds_read_b128 v[116:119], v206
	ds_read_b128 v[120:123], v206
	ds_read_b128 v[124:127], v206

;     __device__ bool next(int i, Unit& u) const { const bool ok = StaticOrder::next(i / 3, u); u.seg = i % 3; return ok; }
; template <class Epi, class Sched>
; __device__ __forceinline__ void gemm_phase(LAS unsigned char* lds, const Gemm g, const Sched& S, const Epi& E) {
;     ...
;         const bool has_next = S.next(ui + 1, nxt);
;         const char* nA = has_next ? (const char*)g.A + (size_t)(g.fix ? 0 : nxt.pm) * tstepA + (size_t)S.koff(nxt) * 2 : cA; const char* nB = has_next ? (const char*)g.Bt + (size_t)(g.fix ? 0 : nxt.pn) * tstepB + (size_t)S.koff(nxt) * 2 : cB;
;     ...
; #pragma unroll
;         for (int a = 0; a < 2; ++a)
; #pragma unroll
;             for (int b = 0; b < 2; ++b)
; #pragma unroll
;                 for (int m = 0; m < 4; ++m)
; #pragma unroll
;                     for (int n = 0; n < 2; ++n) acc[a][b][m][n] = (f32x4){0.f, 0.f, 0.f, 0.f};
;         cur = nxt; cA = nA; cB = nB; ++ui;
;         if (Sched::SEGMENTED) nt = S.nt(cur);
.LBB0_381:
	s_ashr_i32 s49, s48, 31
	s_lshl_b64 s[40:41], s[48:49], 20
	s_add_u32 s52, s90, s40
	s_addc_u32 s53, s91, s41
	s_and_b64 s[40:41], s[38:39], exec
	s_cselect_b32 s20, s53, s1
	s_cselect_b32 s27, s52, s0
	s_ashr_i32 s51, s50, 31
	s_lshl_b64 s[40:41], s[50:51], 20
	v_readlane_b32 s54, v253, 19
	v_readlane_b32 s55, v253, 20
	s_add_u32 s54, s54, s40
	s_addc_u32 s55, s55, s41
	s_and_b64 s[40:41], s[38:39], exec
	s_cselect_b32 s49, s55, s23
	s_cselect_b32 s51, s54, s22
	s_add_u32 s0, s0, 0x80080
	s_addc_u32 s1, s1, 0
	s_add_u32 s63, s22, 0x100
	v_mov_b32_e32 v0, 0
	s_addc_u32 s64, s23, 0
	s_mov_b32 s65, -2
	v_mov_b32_e32 v206, 0x23000
	ds_read_b128 v[0:3], v206
	ds_read_b128 v[4:7], v206
	ds_read_b128 v[8:11], v206
	ds_read_b128 v[12:15], v206
	ds_read_b128 v[16:19], v206
	ds_read_b128 v[20:23], v206
	ds_read_b128 v[24:27], v206
	ds_read_b128 v[28:31], v206
	ds_read_b128 v[32:35], v206
	ds_read_b128 v[36:39], v206
	ds_read_b128 v[40:43], v206
	ds_read_b128 v[44:47], v206
	ds_read_b128 v[48:51], v206
	ds_read_b128 v[52:55], v206
	ds_read_b128 v[56:59], v206
	ds_read_b128 v[60:63], v206
	ds_read_b128 v[64:67], v206
	ds_read_b128 v[68:71], v206
	ds_read_b128 v[72:75], v206
	ds_read_b128 v[76:79], v206
	ds_read_b128 v[80:83], v206
	ds_read_b128 v[84:87], v206
	ds_read_b128 v[88:91], v206
	ds_read_b128 v[92:95], v206
	ds_read_b128 v[96:99], v206
	ds_read_b128 v[100:103], v206
	ds_read_b128 v[104:107], v206
	ds_read_b128 v[108:111], v206
	ds_read_b128 v[112:115], v206
	ds_read_b128 v[116:119], v206
	ds_read_b128 v[120:123], v206
	ds_read_b128 v[124:127], v206

;     __device__ bool next(int i, Unit& u) const { const bool ok = StaticOrder::next(i / 3, u); u.seg = i % 3; return ok; }
; template <class Epi, class Sched>
; __device__ __forceinline__ void gemm_phase(LAS unsigned char* lds, const Gemm g, const Sched& S, const Epi& E) {
;     ...
;         const bool has_next = S.next(ui + 1, nxt);
;         const char* nA = has_next ? (const char*)g.A + (size_t)(g.fix ? 0 : nxt.pm) * tstepA + (size_t)S.koff(nxt) * 2 : cA; const char* nB = has_next ? (const char*)g.Bt + (size_t)(g.fix ? 0 : nxt.pn) * tstepB + (size_t)S.koff(nxt) * 2 : cB;
;     ...
; #pragma unroll
;         for (int a = 0; a < 2; ++a)
; #pragma unroll
;             for (int b = 0; b < 2; ++b)
; #pragma unroll
;                 for (int m = 0; m < 4; ++m)
; #pragma unroll
;                     for (int n = 0; n < 2; ++n) acc[a][b][m][n] = (f32x4){0.f, 0.f, 0.f, 0.f};
;         cur = nxt; cA = nA; cB = nB; ++ui;
;         if (Sched::SEGMENTED) nt = S.nt(cur);
.LBB0_678:
	s_add_u32 vcc_lo, s54, 0x100
	v_mov_b32_e32 v0, 0
	s_addc_u32 vcc_hi, s55, 0
	s_mov_b32 s4, -2
	s_waitcnt lgkmcnt(0)
	v_mov_b32_e32 v206, 0x23000
	ds_read_b128 v[0:3], v206
	ds_read_b128 v[4:7], v206
	ds_read_b128 v[8:11], v206
	ds_read_b128 v[12:15], v206
	ds_read_b128 v[16:19], v206
	ds_read_b128 v[20:23], v206
	ds_read_b128 v[24:27], v206
	ds_read_b128 v[28:31], v206
	ds_read_b128 v[32:35], v206
	ds_read_b128 v[36:39], v206
	ds_read_b128 v[40:43], v206
	ds_read_b128 v[44:47], v206
	ds_read_b128 v[48:51], v206
	ds_read_b128 v[52:55], v206
	ds_read_b128 v[56:59], v206
	ds_read_b128 v[60:63], v206
	ds_read_b128 v[64:67], v206
	ds_read_b128 v[68:71], v206
	ds_read_b128 v[72:75], v206
	ds_read_b128 v[76:79], v206
	ds_read_b128 v[80:83], v206
	ds_read_b128 v[84:87], v206
	ds_read_b128 v[88:91], v206
	ds_read_b128 v[92:95], v206
	ds_read_b128 v[96:99], v206
	ds_read_b128 v[100:103], v206
	ds_read_b128 v[104:107], v206
	ds_read_b128 v[108:111], v206
	ds_read_b128 v[112:115], v206
	ds_read_b128 v[116:119], v206
	ds_read_b128 v[120:123], v206
	ds_read_b128 v[124:127], v206

; template <class Epi, class Sched>
; __device__ __forceinline__ void gemm_phase(LAS unsigned char* lds, const Gemm g, const Sched& S, const Epi& E) {
;     ...
;         const char* nA = has_next ? (const char*)g.A + (size_t)(g.fix ? 0 : nxt.pm) * tstepA + (size_t)S.koff(nxt) * 2 : cA; const char* nB = has_next ? (const char*)g.Bt + (size_t)(g.fix ? 0 : nxt.pn) * tstepB + (size_t)S.koff(nxt) * 2 : cB;
;     ...
; #pragma unroll
;         for (int a = 0; a < 2; ++a)
; #pragma unroll
;             for (int b = 0; b < 2; ++b)
; #pragma unroll
;                 for (int m = 0; m < 4; ++m)
; #pragma unroll
;                     for (int n = 0; n < 2; ++n) acc[a][b][m][n] = (f32x4){0.f, 0.f, 0.f, 0.f};
;         cur = nxt; cA = nA; cB = nB; ++ui;
;         if (Sched::SEGMENTED) nt = S.nt(cur);
.LBB0_744:
	s_ashr_i32 s45, s44, 31
	s_lshl_b64 s[48:49], s[44:45], 20
	s_add_u32 s48, s90, s48
	s_addc_u32 s49, s91, s49
	s_and_b64 s[50:51], s[38:39], exec
	s_cselect_b32 s45, s49, s23
	s_cselect_b32 s60, s48, s22
	s_ashr_i32 s47, s46, 31
	s_lshl_b64 s[50:51], s[46:47], 20
	s_add_u32 s50, s28, s50
	s_addc_u32 s51, s30, s51
	s_and_b64 s[54:55], s[38:39], exec
	s_cselect_b32 s47, s51, s53
	s_cselect_b32 s61, s50, s52
	s_add_u32 s22, s22, 0x80080
	s_addc_u32 s23, s23, 0
	s_add_u32 s65, s52, 0x100
	v_mov_b32_e32 v0, 0
	s_addc_u32 s92, s53, 0
	s_mov_b32 s94, -2
	v_mov_b32_e32 v206, 0x23000
	ds_read_b128 v[0:3], v206
	ds_read_b128 v[4:7], v206
	ds_read_b128 v[8:11], v206
	ds_read_b128 v[12:15], v206
	ds_read_b128 v[16:19], v206
	ds_read_b128 v[20:23], v206
	ds_read_b128 v[24:27], v206
	ds_read_b128 v[28:31], v206
	ds_read_b128 v[32:35], v206
	ds_read_b128 v[36:39], v206
	ds_read_b128 v[40:43], v206
	ds_read_b128 v[44:47], v206
	ds_read_b128 v[48:51], v206
	ds_read_b128 v[52:55], v206
	ds_read_b128 v[56:59], v206
	ds_read_b128 v[60:63], v206
	ds_read_b128 v[64:67], v206
	ds_read_b128 v[68:71], v206
	ds_read_b128 v[72:75], v206
	ds_read_b128 v[76:79], v206
	ds_read_b128 v[80:83], v206
	ds_read_b128 v[84:87], v206
	ds_read_b128 v[88:91], v206
	ds_read_b128 v[92:95], v206
	ds_read_b128 v[96:99], v206
	ds_read_b128 v[100:103], v206
	ds_read_b128 v[104:107], v206
	ds_read_b128 v[108:111], v206
	ds_read_b128 v[112:115], v206
	ds_read_b128 v[116:119], v206
	ds_read_b128 v[120:123], v206
	ds_read_b128 v[124:127], v206
